# grid barrier: non-leader workgroups poll the top-level generation word directly instead of their XCD's relay word (one hop less per barrier)
# speedup vs baseline: 1.0136x; 1.0136x over previous
; __device__ __forceinline__ unsigned xb_ld(unsigned* p)              { return __hip_atomic_load(p, __ATOMIC_RELAXED, __HIP_MEMORY_SCOPE_AGENT); }
; __device__ __forceinline__ unsigned xb_add(unsigned* p, unsigned v) { return __hip_atomic_fetch_add(p, v, __ATOMIC_RELAXED, __HIP_MEMORY_SCOPE_AGENT); }
; #define XB_SPIN(cond, bar) do { unsigned _sp = 0; while (cond) { __builtin_amdgcn_s_sleep(1); \
;     if ((++_sp & 255u) == 0u) { if (xb_ld(&(bar)[XB_TMO])) break; if (_sp > XB_SPIN_CAP) { atomicAdd(&(bar)[XB_TMO], 1u); break; } } } } while (0)
; __device__ __forceinline__ void xcd_barrier_complete(unsigned* bar, unsigned x, unsigned& nloc, unsigned& nx) {
;     ...
;         for (unsigned j = 0; j < 16; ++j) { const unsigned c = xb_ld(&bar[XB_XCNT(j)]); sum += c; cnt += (c > 0u) ? 1u : 0u; mine = (j == x) ? c : mine; }
;         if (sum == G) break;
;         __builtin_amdgcn_s_sleep(1);
;         if ((++sp & 255u) == 0u) { if (xb_ld(&bar[XB_TMO])) break; if (sp > XB_SPIN_CAP) { atomicAdd(&bar[XB_TMO], 1u); break; } }
;     }
;     nloc = mine > 0u ? mine : 1u; nx = cnt > 0u ? cnt : 1u;
; }
; __device__ __forceinline__ void xcd_barrier(XcdBarrier& b) {
;     asm volatile("s_waitcnt vmcnt(0)" ::: "memory");
;     __syncthreads();
;     if (threadIdx.x == 0) {
;         unsigned* bar = b.bar;
;         __builtin_amdgcn_s_waitcnt(0);
;         if (b.nloc == 0u) xcd_barrier_complete(bar, b.x, b.nloc, b.nx);
;         const unsigned nloc = b.nloc, nx = b.nx;
;         const unsigned old = xb_add(&bar[XB_XSUB(b.x)], 1u);
;         const unsigned gen = old / nloc;
;         if (old + 1u == (gen + 1u) * nloc) {
;             __builtin_amdgcn_fence(__ATOMIC_RELEASE, "agent");
;             asm volatile("s_waitcnt vmcnt(0)" ::: "memory");
;             const unsigned og = xb_add(&bar[XB_TOP], 1u);
;             const unsigned tg = og / nx;
;             if (og + 1u == (tg + 1u) * nx) xb_add(&bar[XB_TOPGEN], 1u);
;             else XB_SPIN(xb_ld(&bar[XB_TOPGEN]) == tg, bar);
;             __builtin_amdgcn_fence(__ATOMIC_ACQUIRE, "agent");
;             xb_add(&bar[XB_XGEN(b.x)], 1u);
;             asm volatile("s_waitcnt vmcnt(0)" ::: "memory");
;         } else {
;             XB_SPIN(xb_ld(&bar[XB_XGEN(b.x)]) == gen, bar);
;             __builtin_amdgcn_fence(__ATOMIC_ACQUIRE, "agent");
;             asm volatile("s_waitcnt vmcnt(0)" ::: "memory");
.LBB0_25:
	s_or_b64 exec, exec, s[12:13]
	s_cmp_eq_u32 s33, 0
	s_cselect_b64 vcc, -1, 0
	s_cmp_eq_u32 s33, 1
	v_cndmask_b32_e32 v19, 0, v16, vcc
	s_cselect_b64 vcc, -1, 0
	s_cmp_eq_u32 s33, 2
	v_cndmask_b32_e32 v19, v19, v4, vcc
	s_cselect_b64 vcc, -1, 0
	s_cmp_eq_u32 s33, 3
	v_cndmask_b32_e32 v19, v19, v5, vcc
	s_cselect_b64 vcc, -1, 0
	s_cmp_eq_u32 s33, 4
	v_cndmask_b32_e32 v19, v19, v6, vcc
	s_cselect_b64 vcc, -1, 0
	s_cmp_eq_u32 s33, 5
	v_cndmask_b32_e32 v19, v19, v7, vcc
	s_cselect_b64 vcc, -1, 0
	s_cmp_eq_u32 s33, 6
	v_cndmask_b32_e32 v19, v19, v8, vcc
	s_cselect_b64 vcc, -1, 0
	s_cmp_eq_u32 s33, 7
	v_cndmask_b32_e32 v19, v19, v9, vcc
	s_cselect_b64 vcc, -1, 0
	s_cmp_eq_u32 s33, 8
	v_cndmask_b32_e32 v19, v19, v10, vcc
	s_cselect_b64 vcc, -1, 0
	s_cmp_eq_u32 s33, 9
	v_cndmask_b32_e32 v19, v19, v11, vcc
	s_cselect_b64 vcc, -1, 0
	s_cmp_eq_u32 s33, 10
	v_cndmask_b32_e32 v19, v19, v12, vcc
	s_cselect_b64 vcc, -1, 0
	s_cmp_eq_u32 s33, 11
	v_cndmask_b32_e32 v19, v19, v13, vcc
	s_cselect_b64 vcc, -1, 0
	s_cmp_eq_u32 s33, 12
	v_cndmask_b32_e32 v19, v19, v14, vcc
	s_cselect_b64 vcc, -1, 0
	s_cmp_eq_u32 s33, 13
	v_cndmask_b32_e32 v19, v19, v15, vcc
	s_cselect_b64 vcc, -1, 0
	s_cmp_eq_u32 s33, 14
	v_cndmask_b32_e32 v19, v19, v2, vcc
	s_cselect_b64 vcc, -1, 0
	s_cmp_eq_u32 s33, 15
	v_cndmask_b32_e32 v19, v19, v3, vcc
	s_cselect_b64 vcc, -1, 0
	v_cndmask_b32_e32 v19, v19, v1, vcc
	v_cmp_ne_u32_e32 vcc, 0, v16
	v_max_u32_e32 v130, 1, v19
	s_waitcnt vmcnt(0)
	v_readfirstlane_b32 s10, v18
	v_cndmask_b32_e64 v16, 0, 1, vcc
	v_cmp_ne_u32_e32 vcc, 0, v4
	s_nop 1
	v_addc_co_u32_e32 v4, vcc, 0, v16, vcc
	v_cmp_ne_u32_e32 vcc, 0, v5
	s_nop 1
	v_cndmask_b32_e64 v5, 0, 1, vcc
	v_cmp_ne_u32_e32 vcc, 0, v6
	v_cvt_f32_u32_e32 v6, v130
	s_nop 0
	v_addc_co_u32_e32 v4, vcc, v4, v5, vcc
	v_cmp_ne_u32_e32 vcc, 0, v7
	s_nop 1
	v_cndmask_b32_e64 v5, 0, 1, vcc
	v_cmp_ne_u32_e32 vcc, 0, v8
	s_nop 1
	v_addc_co_u32_e32 v4, vcc, v4, v5, vcc
	v_cmp_ne_u32_e32 vcc, 0, v9
	s_nop 1
	v_cndmask_b32_e64 v5, 0, 1, vcc
	v_cmp_ne_u32_e32 vcc, 0, v10
	s_nop 1
	v_addc_co_u32_e32 v4, vcc, v4, v5, vcc
	v_cmp_ne_u32_e32 vcc, 0, v11
	s_nop 1
	v_cndmask_b32_e64 v5, 0, 1, vcc
	v_cmp_ne_u32_e32 vcc, 0, v12
	s_nop 1
	v_addc_co_u32_e32 v4, vcc, v4, v5, vcc
	v_cmp_ne_u32_e32 vcc, 0, v13
	s_nop 1
	v_cndmask_b32_e64 v5, 0, 1, vcc
	v_cmp_ne_u32_e32 vcc, 0, v14
	s_nop 1
	v_addc_co_u32_e32 v4, vcc, v4, v5, vcc
	v_cmp_ne_u32_e32 vcc, 0, v15
	s_nop 1
	v_cndmask_b32_e64 v5, 0, 1, vcc
	v_cmp_ne_u32_e32 vcc, 0, v2
	s_nop 1
	v_addc_co_u32_e32 v2, vcc, v4, v5, vcc
	v_rcp_iflag_f32_e32 v4, v6
	v_cmp_ne_u32_e32 vcc, 0, v3
	s_nop 1
	v_cndmask_b32_e64 v3, 0, 1, vcc
	v_cmp_ne_u32_e32 vcc, 0, v1
	s_nop 1
	v_addc_co_u32_e32 v1, vcc, v2, v3, vcc
	v_mul_f32_e32 v2, 0x4f7ffffe, v4
	v_cvt_u32_f32_e32 v2, v2
	v_sub_u32_e32 v4, 0, v130
	v_add_u32_e32 v3, s10, v17
	v_mul_lo_u32 v4, v4, v2
	v_mul_hi_u32 v4, v2, v4
	v_add_u32_e32 v2, v2, v4
	v_mul_hi_u32 v2, v3, v2
	v_mul_lo_u32 v4, v2, v130
	v_sub_u32_e32 v4, v3, v4
	v_add_u32_e32 v5, 1, v2
	v_cmp_ge_u32_e32 vcc, v4, v130
	v_add_u32_e32 v3, 1, v3
	s_nop 0
	v_cndmask_b32_e32 v2, v2, v5, vcc
	v_sub_u32_e32 v5, v4, v130
	v_cndmask_b32_e32 v4, v4, v5, vcc
	v_add_u32_e32 v5, 1, v2
	v_cmp_ge_u32_e32 vcc, v4, v130
	s_nop 1
	v_cndmask_b32_e32 v2, v2, v5, vcc
	v_mul_lo_u32 v4, v130, v2
	v_add_u32_e32 v4, v4, v130
	v_cmp_ne_u32_e32 vcc, v3, v4
	s_and_saveexec_b64 s[10:11], vcc
	s_xor_b64 s[10:11], exec, s[10:11]
	s_cbranch_execz .LBB0_39
	v_mov_b32_e32 v3, 0x3500
	global_load_dword v3, v3, s[36:37] sc1
	s_add_u32 s14, s36, 0x3500
	s_addc_u32 s15, s37, 0
	s_waitcnt vmcnt(0)
	v_cmp_eq_u32_e32 vcc, v3, v2
	s_and_saveexec_b64 s[12:13], vcc
	s_cbranch_execz .LBB0_38
	s_mov_b32 s26, 1
	s_mov_b64 s[16:17], 0
	v_mov_b32_e32 v3, 0
	s_branch .LBB0_29

; __device__ __forceinline__ unsigned xb_ld(unsigned* p)              { return __hip_atomic_load(p, __ATOMIC_RELAXED, __HIP_MEMORY_SCOPE_AGENT); }
; __device__ __forceinline__ unsigned xb_add(unsigned* p, unsigned v) { return __hip_atomic_fetch_add(p, v, __ATOMIC_RELAXED, __HIP_MEMORY_SCOPE_AGENT); }
; #define XB_SPIN(cond, bar) do { unsigned _sp = 0; while (cond) { __builtin_amdgcn_s_sleep(1); \
;     if ((++_sp & 255u) == 0u) { if (xb_ld(&(bar)[XB_TMO])) break; if (_sp > XB_SPIN_CAP) { atomicAdd(&(bar)[XB_TMO], 1u); break; } } } } while (0)
; __device__ __forceinline__ void xcd_barrier(XcdBarrier& b) {
;     asm volatile("s_waitcnt vmcnt(0)" ::: "memory");
;     __syncthreads();
;     if (threadIdx.x == 0) {
;         unsigned* bar = b.bar;
;         __builtin_amdgcn_s_waitcnt(0);
;         if (b.nloc == 0u) xcd_barrier_complete(bar, b.x, b.nloc, b.nx);
;         const unsigned nloc = b.nloc, nx = b.nx;
;         const unsigned old = xb_add(&bar[XB_XSUB(b.x)], 1u);
;         const unsigned gen = old / nloc;
;         if (old + 1u == (gen + 1u) * nloc) {
;             __builtin_amdgcn_fence(__ATOMIC_RELEASE, "agent");
;             asm volatile("s_waitcnt vmcnt(0)" ::: "memory");
;             const unsigned og = xb_add(&bar[XB_TOP], 1u);
;             const unsigned tg = og / nx;
;             if (og + 1u == (tg + 1u) * nx) xb_add(&bar[XB_TOPGEN], 1u);
;             else XB_SPIN(xb_ld(&bar[XB_TOPGEN]) == tg, bar);
;             __builtin_amdgcn_fence(__ATOMIC_ACQUIRE, "agent");
;             xb_add(&bar[XB_XGEN(b.x)], 1u);
;             asm volatile("s_waitcnt vmcnt(0)" ::: "memory");
;         } else {
;             XB_SPIN(xb_ld(&bar[XB_XGEN(b.x)]) == gen, bar);
;             __builtin_amdgcn_fence(__ATOMIC_ACQUIRE, "agent");
;             asm volatile("s_waitcnt vmcnt(0)" ::: "memory");
.LBB0_114:
	s_or_b64 exec, exec, s[8:9]
	v_cvt_f32_u32_e32 v2, v130
	s_waitcnt vmcnt(0)
	v_readfirstlane_b32 s6, v1
	v_rcp_iflag_f32_e32 v2, v2
	s_nop 0
	v_add_u32_e32 v0, s6, v0
	v_add_u32_e32 v4, 1, v0
	v_mul_f32_e32 v1, 0x4f7ffffe, v2
	v_cvt_u32_f32_e32 v1, v1
	v_sub_u32_e32 v2, 0, v130
	v_mul_lo_u32 v2, v2, v1
	v_mul_hi_u32 v2, v1, v2
	v_add_u32_e32 v1, v1, v2
	v_mul_hi_u32 v1, v0, v1
	v_mul_lo_u32 v2, v1, v130
	v_sub_u32_e32 v0, v0, v2
	v_add_u32_e32 v3, 1, v1
	v_cmp_ge_u32_e32 vcc, v0, v130
	v_sub_u32_e32 v2, v0, v130
	s_nop 0
	v_cndmask_b32_e32 v1, v1, v3, vcc
	v_cndmask_b32_e32 v0, v0, v2, vcc
	v_add_u32_e32 v2, 1, v1
	v_cmp_ge_u32_e32 vcc, v0, v130
	s_nop 1
	v_cndmask_b32_e32 v0, v1, v2, vcc
	v_mad_u64_u32 v[2:3], s[6:7], v130, v0, v[130:131]
	v_cmp_ne_u32_e32 vcc, v4, v2
	s_and_saveexec_b64 s[6:7], vcc
	s_xor_b64 s[6:7], exec, s[6:7]
	s_cbranch_execz .LBB0_128
	v_mov_b32_e32 v1, 0x3500
	global_load_dword v1, v1, s[36:37] sc1
	s_add_u32 s10, s36, 0x3500
	s_addc_u32 s11, s37, 0
	s_waitcnt vmcnt(0)
	v_cmp_eq_u32_e32 vcc, v1, v0
	s_and_saveexec_b64 s[8:9], vcc
	s_cbranch_execz .LBB0_127
	s_mov_b32 s22, 1
	s_mov_b64 s[12:13], 0
	v_mov_b32_e32 v1, 0
	s_branch .LBB0_118
